# speedup vs baseline: 1.0066x; 1.0066x over previous
; #define PG8_STAGE(bufoff, gbase, voff) do { _Pragma("unroll") for (int _i = 0; _i < 2; ++_i) \
;         __builtin_amdgcn_global_load_lds((const unsigned*)((const char*)(gbase) + (voff)[_i]), (PG8_LAS unsigned*)(lds + (bufoff) + ldsw + _i * 8192), 16, 0, 0); } while (0)
; #define PG8_LDA(dst, b, h) do { _Pragma("unroll") for (int m = 0; m < 4; ++m) _Pragma("unroll") for (int k = 0; k < 2; ++k) dst[m][k] = *(const PG8_LAS bf16x8*)(lds + PG8_SA(b, h) + aoff + m * 2048 + k * 1024); } while (0)
; #define PG8_LDB(dst, b, h) do { _Pragma("unroll") for (int n = 0; n < 2; ++n) _Pragma("unroll") for (int k = 0; k < 2; ++k) dst[n][k] = *(const PG8_LAS bf16x8*)(lds + PG8_SB(b, h) + boff + n * 2048 + k * 1024); } while (0)
; #define PG8_MMA(ai, bj, At, Bt) do { __builtin_amdgcn_s_setprio(1); _Pragma("unroll") for (int m = 0; m < 4; ++m) _Pragma("unroll") for (int n = 0; n < 2; ++n) _Pragma("unroll") for (int k = 0; k < 2; ++k) \
;         acc[ai][bj][m][n] = __builtin_amdgcn_mfma_f32_16x16x32_bf16(Bt[n][k], At[m][k], acc[ai][bj][m][n], 0, 0, 0); __builtin_amdgcn_s_setprio(0); } while (0)
; #define PG8_WAIT_V(n) asm volatile("s_waitcnt vmcnt(" #n ")" ::: "memory")
; #define PG8_WAIT_L(n) asm volatile("s_waitcnt lgkmcnt(" #n ")" ::: "memory")
; #define PG8_BAR __builtin_amdgcn_s_barrier()
; #define PG8_SCHED __builtin_amdgcn_sched_barrier(0)
; template <class Epi, class Sched, bool ALIGN_EPI = false, bool SP2 = false>
; __device__ __forceinline__ void gemm_phase(PG8_LAS unsigned char* lds, const Gemm g, const Sched& S, const Epi& E) {
;     ...
;             PG8_LDB(B0, 0, 0); PG8_LDB(B1, 0, 1); PG8_SCHED; PG8_LDA(At, 0, 0); PG8_STAGE(PG8_SA(1, 1), a1 + hstepA, voffA);
;             PG8_WAIT_V(8); PG8_WAIT_L(0); PG8_BAR; PG8_MMA(0, 0, At, B0); PG8_MMA(0, 1, At, B1); PG8_BAR; PG8_SCHED;
;             PG8_LDA(At, 0, 1); PG8_STAGE(PG8_SB(0, 0), b2, voffB); PG8_STAGE(PG8_SB(0, 1), b2 + hstep, voffB); PG8_STAGE(PG8_SA(0, 0), a2, voffA);
;             PG8_WAIT_V(8); PG8_WAIT_L(0); PG8_BAR; PG8_MMA(1, 0, At, B0); PG8_MMA(1, 1, At, B1); PG8_BAR; PG8_SCHED;
.Lpf_skip:
	s_add_u32 s12, s10, 0xfffc0080
	s_addc_u32 s13, s11, -1
	s_add_i32 s94, 0, 0x10000
	s_cmp_eq_u32 vcc_lo, 12
	s_cselect_b32 s45, s21, s13
	s_cselect_b32 s44, s28, s12
	v_add_u32_e32 v0, s94, v179
	s_cselect_b32 s13, s43, s63
	s_cselect_b32 s12, s46, s47
	s_add_i32 vcc_hi, 0, 0x14000
	ds_read_b128 v[130:133], v0
	ds_read_b128 v[134:137], v0 offset:1024
	ds_read_b128 v[138:141], v0 offset:2048
	ds_read_b128 v[142:145], v0 offset:3072
	v_add_u32_e32 v0, vcc_hi, v179
	ds_read_b128 v[146:149], v0
	ds_read_b128 v[170:173], v0 offset:1024
	ds_read_b128 v[190:193], v0 offset:2048
	ds_read_b128 v[194:197], v0 offset:3072
	v_lshl_add_u64 v[150:151], s[10:11], 0, v[162:163]
	s_add_i32 m0, s17, 0xc000
	ds_read_b128 v[198:201], v186
	ds_read_b128 v[202:205], v186 offset:1024
	ds_read_b128 v[206:209], v186 offset:2048
	ds_read_b128 v[210:213], v186 offset:3072
	ds_read_b128 v[214:217], v186 offset:4096
	ds_read_b128 v[218:221], v186 offset:5120
	ds_read_b128 v[222:225], v186 offset:6144
	ds_read_b128 v[226:229], v186 offset:7168
	s_cmp_eq_u32 s87, 1
	s_cbranch_scc0 .Lpe_noe
	global_load_lds_dwordx4 v[150:151], off
	v_lshl_add_u64 v[150:151], s[10:11], 0, v[164:165]
	s_add_i32 m0, s17, 0xe000
	s_nop 0
	global_load_lds_dwordx4 v[150:151], off
.Lpe_noe:
	s_waitcnt vmcnt(24)
	s_waitcnt lgkmcnt(0)
	s_barrier
	s_setprio 1
	s_waitcnt lgkmcnt(0)
	v_mfma_f32_16x16x32_bf16 v[126:129], v[130:133], v[198:201], 0
	v_mfma_f32_16x16x32_bf16 v[122:125], v[138:141], v[198:201], 0
	v_mfma_f32_16x16x32_bf16 v[110:113], v[130:133], v[206:209], 0
	v_mfma_f32_16x16x32_bf16 v[106:109], v[138:141], v[206:209], 0
	v_mfma_f32_16x16x32_bf16 v[94:97], v[130:133], v[214:217], 0
	v_mfma_f32_16x16x32_bf16 v[90:93], v[138:141], v[214:217], 0
	v_mfma_f32_16x16x32_bf16 v[78:81], v[130:133], v[222:225], 0
	v_mfma_f32_16x16x32_bf16 v[74:77], v[138:141], v[222:225], 0
	v_mfma_f32_16x16x32_bf16 v[126:129], v[134:137], v[202:205], v[126:129]
	v_mfma_f32_16x16x32_bf16 v[122:125], v[142:145], v[202:205], v[122:125]
	v_mfma_f32_16x16x32_bf16 v[110:113], v[134:137], v[210:213], v[110:113]
	v_mfma_f32_16x16x32_bf16 v[106:109], v[142:145], v[210:213], v[106:109]
	v_mfma_f32_16x16x32_bf16 v[94:97], v[134:137], v[218:221], v[94:97]
	v_mfma_f32_16x16x32_bf16 v[90:93], v[142:145], v[218:221], v[90:93]
	v_mfma_f32_16x16x32_bf16 v[78:81], v[134:137], v[226:229], v[78:81]
	v_mfma_f32_16x16x32_bf16 v[74:77], v[142:145], v[226:229], v[74:77]
	s_setprio 0
	s_setprio 1
	v_mfma_f32_16x16x32_bf16 v[118:121], v[146:149], v[198:201], 0
	v_mfma_f32_16x16x32_bf16 v[114:117], v[190:193], v[198:201], 0
	v_mfma_f32_16x16x32_bf16 v[102:105], v[146:149], v[206:209], 0
	v_mfma_f32_16x16x32_bf16 v[98:101], v[190:193], v[206:209], 0
	v_mfma_f32_16x16x32_bf16 v[86:89], v[146:149], v[214:217], 0
	v_mfma_f32_16x16x32_bf16 v[82:85], v[190:193], v[214:217], 0
	v_mfma_f32_16x16x32_bf16 v[70:73], v[146:149], v[222:225], 0
	v_mfma_f32_16x16x32_bf16 v[66:69], v[190:193], v[222:225], 0
	v_mfma_f32_16x16x32_bf16 v[118:121], v[170:173], v[202:205], v[118:121]
	v_mfma_f32_16x16x32_bf16 v[114:117], v[194:197], v[202:205], v[114:117]
	v_mfma_f32_16x16x32_bf16 v[102:105], v[170:173], v[210:213], v[102:105]
	v_mfma_f32_16x16x32_bf16 v[98:101], v[194:197], v[210:213], v[98:101]
	v_mfma_f32_16x16x32_bf16 v[86:89], v[170:173], v[218:221], v[86:89]
	v_mfma_f32_16x16x32_bf16 v[82:85], v[194:197], v[218:221], v[82:85]
	v_mfma_f32_16x16x32_bf16 v[70:73], v[170:173], v[226:229], v[70:73]
	v_mfma_f32_16x16x32_bf16 v[66:69], v[194:197], v[226:229], v[66:69]
	s_setprio 0
	s_barrier
	s_add_i32 s94, s94, s16
	v_lshl_add_u64 v[150:151], s[12:13], 0, v[156:157]
	s_mov_b32 m0, s94
	ds_read_b128 v[198:201], v186 offset:16384
	ds_read_b128 v[202:205], v186 offset:17408
	ds_read_b128 v[206:209], v186 offset:18432
	ds_read_b128 v[210:213], v186 offset:19456
	ds_read_b128 v[214:217], v186 offset:20480
	ds_read_b128 v[218:221], v186 offset:21504
	ds_read_b128 v[222:225], v186 offset:22528
	ds_read_b128 v[226:229], v186 offset:23552
	global_load_lds_dwordx4 v[150:151], off
	s_add_i32 m0, s94, 0x2000
	s_add_u32 s94, s12, 0x40000
	v_lshl_add_u64 v[166:167], s[12:13], 0, v[160:161]
	s_addc_u32 s95, s13, 0
	s_add_i32 vcc_hi, vcc_hi, s16
	global_load_lds_dwordx4 v[166:167], off
	v_lshl_add_u64 v[230:231], s[94:95], 0, v[156:157]
	s_mov_b32 m0, vcc_hi
	v_lshl_add_u64 v[232:233], s[44:45], 0, v[158:159]
	global_load_lds_dwordx4 v[230:231], off
	v_lshl_add_u64 v[230:231], s[94:95], 0, v[160:161]
	s_add_i32 m0, vcc_hi, 0x2000
	s_nop 0
	global_load_lds_dwordx4 v[230:231], off
	v_lshl_add_u64 v[230:231], s[44:45], 0, v[154:155]
	s_mov_b32 m0, s17
	s_nop 0
	global_load_lds_dwordx4 v[230:231], off
	s_mov_b32 m0, s51
	s_nop 0
	global_load_lds_dwordx4 v[232:233], off
	s_cmp_eq_u32 s87, 1
	s_cbranch_scc1 .Lpe_w2_strict
	s_waitcnt vmcnt(24)
	s_branch .Lpe_w2_done
; #define PG8_STAGE(bufoff, gbase, voff) do { _Pragma("unroll") for (int _i = 0; _i < 2; ++_i) \
;         __builtin_amdgcn_global_load_lds((const unsigned*)((const char*)(gbase) + (voff)[_i]), (PG8_LAS unsigned*)(lds + (bufoff) + ldsw + _i * 8192), 16, 0, 0); } while (0)
; #define PG8_LDA(dst, b, h) do { _Pragma("unroll") for (int m = 0; m < 4; ++m) _Pragma("unroll") for (int k = 0; k < 2; ++k) dst[m][k] = *(const PG8_LAS bf16x8*)(lds + PG8_SA(b, h) + aoff + m * 2048 + k * 1024); } while (0)
; #define PG8_LDB(dst, b, h) do { _Pragma("unroll") for (int n = 0; n < 2; ++n) _Pragma("unroll") for (int k = 0; k < 2; ++k) dst[n][k] = *(const PG8_LAS bf16x8*)(lds + PG8_SB(b, h) + boff + n * 2048 + k * 1024); } while (0)
; #define PG8_MMA(ai, bj, At, Bt) do { __builtin_amdgcn_s_setprio(1); _Pragma("unroll") for (int m = 0; m < 4; ++m) _Pragma("unroll") for (int n = 0; n < 2; ++n) _Pragma("unroll") for (int k = 0; k < 2; ++k) \
;         acc[ai][bj][m][n] = __builtin_amdgcn_mfma_f32_16x16x32_bf16(Bt[n][k], At[m][k], acc[ai][bj][m][n], 0, 0, 0); __builtin_amdgcn_s_setprio(0); } while (0)
; #define PG8_WAIT_V(n) asm volatile("s_waitcnt vmcnt(" #n ")" ::: "memory")
; #define PG8_WAIT_L(n) asm volatile("s_waitcnt lgkmcnt(" #n ")" ::: "memory")
; #define PG8_BAR __builtin_amdgcn_s_barrier()
; #define PG8_SCHED __builtin_amdgcn_sched_barrier(0)
; template <class Epi, class Sched, bool ALIGN_EPI = false, bool SP2 = false>
; __device__ __forceinline__ void gemm_phase(PG8_LAS unsigned char* lds, const Gemm g, const Sched& S, const Epi& E) {
;     ...
;             PG8_WAIT_V(8); PG8_WAIT_L(0); PG8_BAR; PG8_MMA(1, 0, At, B0); PG8_MMA(1, 1, At, B1); PG8_BAR; PG8_SCHED;
;             PG8_LDB(B0, 1, 0); PG8_LDB(B1, 1, 1); PG8_SCHED; PG8_LDA(At, 1, 0); PG8_STAGE(PG8_SA(0, 1), a2 + hstepA, voffA);
;             PG8_WAIT_V(8); PG8_WAIT_L(0); PG8_BAR; PG8_MMA(0, 0, At, B0); PG8_MMA(0, 1, At, B1); PG8_BAR; PG8_SCHED;
;             PG8_LDA(At, 1, 1); PG8_STAGE(PG8_SB(1, 0), b3, voffB); PG8_STAGE(PG8_SB(1, 1), b3 + hstep, voffB); PG8_STAGE(PG8_SA(1, 0), a3, voffA);
.Lpe_w2_strict:
	s_waitcnt vmcnt(8)
.Lpe_w2_done:
	s_waitcnt lgkmcnt(0)
	s_barrier
	s_setprio 1
	s_waitcnt lgkmcnt(0)
	v_mfma_f32_16x16x32_bf16 v[62:65], v[130:133], v[198:201], 0
	v_mfma_f32_16x16x32_bf16 v[58:61], v[138:141], v[198:201], 0
	v_mfma_f32_16x16x32_bf16 v[46:49], v[130:133], v[206:209], 0
	v_mfma_f32_16x16x32_bf16 v[42:45], v[138:141], v[206:209], 0
	v_mfma_f32_16x16x32_bf16 v[30:33], v[130:133], v[214:217], 0
	v_mfma_f32_16x16x32_bf16 v[26:29], v[138:141], v[214:217], 0
	v_mfma_f32_16x16x32_bf16 v[14:17], v[130:133], v[222:225], 0
	v_mfma_f32_16x16x32_bf16 v[10:13], v[138:141], v[222:225], 0
	v_mfma_f32_16x16x32_bf16 v[62:65], v[134:137], v[202:205], v[62:65]
	v_mfma_f32_16x16x32_bf16 v[58:61], v[142:145], v[202:205], v[58:61]
	v_mfma_f32_16x16x32_bf16 v[46:49], v[134:137], v[210:213], v[46:49]
	v_mfma_f32_16x16x32_bf16 v[42:45], v[142:145], v[210:213], v[42:45]
	v_mfma_f32_16x16x32_bf16 v[30:33], v[134:137], v[218:221], v[30:33]
	v_mfma_f32_16x16x32_bf16 v[26:29], v[142:145], v[218:221], v[26:29]
	v_mfma_f32_16x16x32_bf16 v[14:17], v[134:137], v[226:229], v[14:17]
	v_mfma_f32_16x16x32_bf16 v[10:13], v[142:145], v[226:229], v[10:13]
	s_setprio 0
	s_setprio 1
	v_mfma_f32_16x16x32_bf16 v[54:57], v[146:149], v[198:201], 0
	v_mfma_f32_16x16x32_bf16 v[50:53], v[190:193], v[198:201], 0
	v_mfma_f32_16x16x32_bf16 v[38:41], v[146:149], v[206:209], 0
	v_mfma_f32_16x16x32_bf16 v[34:37], v[190:193], v[206:209], 0
	v_mfma_f32_16x16x32_bf16 v[22:25], v[146:149], v[214:217], 0
	v_mfma_f32_16x16x32_bf16 v[18:21], v[190:193], v[214:217], 0
	v_mfma_f32_16x16x32_bf16 v[6:9], v[146:149], v[222:225], 0
	v_mfma_f32_16x16x32_bf16 v[2:5], v[190:193], v[222:225], 0
	v_mfma_f32_16x16x32_bf16 v[54:57], v[170:173], v[202:205], v[54:57]
	v_mfma_f32_16x16x32_bf16 v[50:53], v[194:197], v[202:205], v[50:53]
	v_mfma_f32_16x16x32_bf16 v[38:41], v[170:173], v[210:213], v[38:41]
	v_mfma_f32_16x16x32_bf16 v[34:37], v[194:197], v[210:213], v[34:37]
	v_mfma_f32_16x16x32_bf16 v[22:25], v[170:173], v[218:221], v[22:25]
	v_mfma_f32_16x16x32_bf16 v[18:21], v[194:197], v[218:221], v[18:21]
	v_mfma_f32_16x16x32_bf16 v[6:9], v[170:173], v[226:229], v[6:9]
	v_mfma_f32_16x16x32_bf16 v[2:5], v[194:197], v[226:229], v[2:5]
	s_setprio 0
	s_barrier
	s_add_i32 s94, 0, 0x18000
	v_add_u32_e32 v0, s94, v179
	s_add_i32 s95, 0, 0x1c000
	ds_read_b128 v[130:133], v0
	ds_read_b128 v[134:137], v0 offset:1024
	ds_read_b128 v[138:141], v0 offset:2048
	ds_read_b128 v[142:145], v0 offset:3072
	v_add_u32_e32 v0, s95, v179
	ds_read_b128 v[146:149], v0
	ds_read_b128 v[170:173], v0 offset:1024
	ds_read_b128 v[190:193], v0 offset:2048
	ds_read_b128 v[194:197], v0 offset:3072
	s_add_u32 s44, s44, 0x40000
	s_addc_u32 s45, s45, 0
	s_mov_b32 m0, s35
	v_lshl_add_u64 v[234:235], s[44:45], 0, v[154:155]
	ds_read_b128 v[198:201], v186 offset:32768
	ds_read_b128 v[202:205], v186 offset:33792
	ds_read_b128 v[206:209], v186 offset:34816
	ds_read_b128 v[210:213], v186 offset:35840
	ds_read_b128 v[214:217], v186 offset:36864
	ds_read_b128 v[218:221], v186 offset:37888
	ds_read_b128 v[222:225], v186 offset:38912
	ds_read_b128 v[226:229], v186 offset:39936
	global_load_lds_dwordx4 v[234:235], off
	v_lshl_add_u64 v[234:235], s[44:45], 0, v[158:159]
	s_mov_b32 m0, s30
	s_nop 0
	global_load_lds_dwordx4 v[234:235], off
	s_cmp_eq_u32 s87, 1
	s_cbranch_scc1 .Lpe_w3_strict
	s_waitcnt vmcnt(24)
	s_branch .Lpe_w3_done

; #define PG8_STAGE(bufoff, gbase, voff) do { _Pragma("unroll") for (int _i = 0; _i < 2; ++_i) \
;         __builtin_amdgcn_global_load_lds((const unsigned*)((const char*)(gbase) + (voff)[_i]), (PG8_LAS unsigned*)(lds + (bufoff) + ldsw + _i * 8192), 16, 0, 0); } while (0)
; #define PG8_LDA(dst, b, h) do { _Pragma("unroll") for (int m = 0; m < 4; ++m) _Pragma("unroll") for (int k = 0; k < 2; ++k) dst[m][k] = *(const PG8_LAS bf16x8*)(lds + PG8_SA(b, h) + aoff + m * 2048 + k * 1024); } while (0)
; #define PG8_MMA(ai, bj, At, Bt) do { __builtin_amdgcn_s_setprio(1); _Pragma("unroll") for (int m = 0; m < 4; ++m) _Pragma("unroll") for (int n = 0; n < 2; ++n) _Pragma("unroll") for (int k = 0; k < 2; ++k) \
;         acc[ai][bj][m][n] = __builtin_amdgcn_mfma_f32_16x16x32_bf16(Bt[n][k], At[m][k], acc[ai][bj][m][n], 0, 0, 0); __builtin_amdgcn_s_setprio(0); } while (0)
; #define PG8_WAIT_V(n) asm volatile("s_waitcnt vmcnt(" #n ")" ::: "memory")
; #define PG8_WAIT_L(n) asm volatile("s_waitcnt lgkmcnt(" #n ")" ::: "memory")
; #define PG8_BAR __builtin_amdgcn_s_barrier()
; #define PG8_SCHED __builtin_amdgcn_sched_barrier(0)
; template <class Epi, class Sched, bool ALIGN_EPI = false, bool SP2 = false>
; __device__ __forceinline__ void gemm_phase(PG8_LAS unsigned char* lds, const Gemm g, const Sched& S, const Epi& E) {
;     ...
;             PG8_WAIT_V(8); PG8_WAIT_L(0); PG8_BAR; PG8_MMA(0, 0, At, B0); PG8_MMA(0, 1, At, B1); PG8_BAR; PG8_SCHED;
;             PG8_LDA(At, 1, 1); PG8_STAGE(PG8_SB(1, 0), b3, voffB); PG8_STAGE(PG8_SB(1, 1), b3 + hstep, voffB); PG8_STAGE(PG8_SA(1, 0), a3, voffA);
;             PG8_WAIT_V(8); PG8_WAIT_L(0); PG8_BAR; PG8_MMA(1, 0, At, B0); PG8_MMA(1, 1, At, B1); PG8_BAR; PG8_SCHED;
.Lpe_w3_done:
	s_waitcnt lgkmcnt(0)
	s_barrier
	s_setprio 1
	s_waitcnt lgkmcnt(0)
	v_mfma_f32_16x16x32_bf16 v[126:129], v[130:133], v[198:201], v[126:129]
	v_mfma_f32_16x16x32_bf16 v[122:125], v[138:141], v[198:201], v[122:125]
	v_mfma_f32_16x16x32_bf16 v[110:113], v[130:133], v[206:209], v[110:113]
	v_mfma_f32_16x16x32_bf16 v[106:109], v[138:141], v[206:209], v[106:109]
	v_mfma_f32_16x16x32_bf16 v[94:97], v[130:133], v[214:217], v[94:97]
	v_mfma_f32_16x16x32_bf16 v[90:93], v[138:141], v[214:217], v[90:93]
	v_mfma_f32_16x16x32_bf16 v[78:81], v[130:133], v[222:225], v[78:81]
	v_mfma_f32_16x16x32_bf16 v[74:77], v[138:141], v[222:225], v[74:77]
	v_mfma_f32_16x16x32_bf16 v[126:129], v[134:137], v[202:205], v[126:129]
	v_mfma_f32_16x16x32_bf16 v[122:125], v[142:145], v[202:205], v[122:125]
	v_mfma_f32_16x16x32_bf16 v[110:113], v[134:137], v[210:213], v[110:113]
	v_mfma_f32_16x16x32_bf16 v[106:109], v[142:145], v[210:213], v[106:109]
	v_mfma_f32_16x16x32_bf16 v[94:97], v[134:137], v[218:221], v[94:97]
	v_mfma_f32_16x16x32_bf16 v[90:93], v[142:145], v[218:221], v[90:93]
	v_mfma_f32_16x16x32_bf16 v[78:81], v[134:137], v[226:229], v[78:81]
	v_mfma_f32_16x16x32_bf16 v[74:77], v[142:145], v[226:229], v[74:77]
	s_setprio 0
	s_setprio 1
	v_mfma_f32_16x16x32_bf16 v[118:121], v[146:149], v[198:201], v[118:121]
	v_mfma_f32_16x16x32_bf16 v[114:117], v[190:193], v[198:201], v[114:117]
	v_mfma_f32_16x16x32_bf16 v[102:105], v[146:149], v[206:209], v[102:105]
	v_mfma_f32_16x16x32_bf16 v[98:101], v[190:193], v[206:209], v[98:101]
	v_mfma_f32_16x16x32_bf16 v[86:89], v[146:149], v[214:217], v[86:89]
	v_mfma_f32_16x16x32_bf16 v[82:85], v[190:193], v[214:217], v[82:85]
	v_mfma_f32_16x16x32_bf16 v[70:73], v[146:149], v[222:225], v[70:73]
	v_mfma_f32_16x16x32_bf16 v[66:69], v[190:193], v[222:225], v[66:69]
	v_mfma_f32_16x16x32_bf16 v[118:121], v[170:173], v[202:205], v[118:121]
	v_mfma_f32_16x16x32_bf16 v[114:117], v[194:197], v[202:205], v[114:117]
	v_mfma_f32_16x16x32_bf16 v[102:105], v[170:173], v[210:213], v[102:105]
	v_mfma_f32_16x16x32_bf16 v[98:101], v[194:197], v[210:213], v[98:101]
	v_mfma_f32_16x16x32_bf16 v[86:89], v[170:173], v[218:221], v[86:89]
	v_mfma_f32_16x16x32_bf16 v[82:85], v[194:197], v[218:221], v[82:85]
	v_mfma_f32_16x16x32_bf16 v[70:73], v[170:173], v[226:229], v[70:73]
	v_mfma_f32_16x16x32_bf16 v[66:69], v[194:197], v[226:229], v[66:69]
	s_setprio 0
	s_barrier
	s_add_i32 s44, s94, s16
	v_lshl_add_u64 v[150:151], v[150:151], 0, s[48:49]
	s_mov_b32 m0, s44
	ds_read_b128 v[198:201], v186 offset:49152
	ds_read_b128 v[202:205], v186 offset:50176
	ds_read_b128 v[206:209], v186 offset:51200
	ds_read_b128 v[210:213], v186 offset:52224
	ds_read_b128 v[214:217], v186 offset:53248
	ds_read_b128 v[218:221], v186 offset:54272
	ds_read_b128 v[222:225], v186 offset:55296
	ds_read_b128 v[226:229], v186 offset:56320
	global_load_lds_dwordx4 v[150:151], off
	s_add_i32 m0, s44, 0x2000
	s_add_u32 s12, s12, 0x40080
	v_lshl_add_u64 v[150:151], v[166:167], 0, s[48:49]
	s_addc_u32 s13, s13, 0
	s_add_i32 s44, s95, s16
	global_load_lds_dwordx4 v[150:151], off
	v_lshl_add_u64 v[150:151], s[12:13], 0, v[156:157]
	s_mov_b32 m0, s44
	s_nop 0
	global_load_lds_dwordx4 v[150:151], off
	v_lshl_add_u64 v[150:151], s[12:13], 0, v[160:161]
	s_add_i32 m0, s44, 0x2000
	s_nop 0
	global_load_lds_dwordx4 v[150:151], off
	v_lshl_add_u64 v[150:151], v[230:231], 0, s[48:49]
	s_mov_b32 m0, s59
	s_nop 0
	global_load_lds_dwordx4 v[150:151], off
	v_lshl_add_u64 v[150:151], v[232:233], 0, s[48:49]
	s_mov_b32 m0, s86
	s_nop 0
	global_load_lds_dwordx4 v[150:151], off
	s_waitcnt vmcnt(8)
	s_waitcnt lgkmcnt(0)
	s_barrier
	s_setprio 1
	s_waitcnt lgkmcnt(0)
	v_mfma_f32_16x16x32_bf16 v[62:65], v[130:133], v[198:201], v[62:65]
	v_mfma_f32_16x16x32_bf16 v[58:61], v[138:141], v[198:201], v[58:61]
	v_mfma_f32_16x16x32_bf16 v[46:49], v[130:133], v[206:209], v[46:49]
	v_mfma_f32_16x16x32_bf16 v[42:45], v[138:141], v[206:209], v[42:45]
	v_mfma_f32_16x16x32_bf16 v[30:33], v[130:133], v[214:217], v[30:33]
	v_mfma_f32_16x16x32_bf16 v[26:29], v[138:141], v[214:217], v[26:29]
	v_mfma_f32_16x16x32_bf16 v[14:17], v[130:133], v[222:225], v[14:17]
	v_mfma_f32_16x16x32_bf16 v[10:13], v[138:141], v[222:225], v[10:13]
	v_mfma_f32_16x16x32_bf16 v[62:65], v[134:137], v[202:205], v[62:65]
	v_mfma_f32_16x16x32_bf16 v[58:61], v[142:145], v[202:205], v[58:61]
	v_mfma_f32_16x16x32_bf16 v[46:49], v[134:137], v[210:213], v[46:49]
	v_mfma_f32_16x16x32_bf16 v[42:45], v[142:145], v[210:213], v[42:45]
	v_mfma_f32_16x16x32_bf16 v[30:33], v[134:137], v[218:221], v[30:33]
	v_mfma_f32_16x16x32_bf16 v[26:29], v[142:145], v[218:221], v[26:29]
	v_mfma_f32_16x16x32_bf16 v[14:17], v[134:137], v[226:229], v[14:17]
	v_mfma_f32_16x16x32_bf16 v[10:13], v[142:145], v[226:229], v[10:13]
	s_setprio 0
	s_setprio 1
	v_mfma_f32_16x16x32_bf16 v[54:57], v[146:149], v[198:201], v[54:57]
	v_mfma_f32_16x16x32_bf16 v[50:53], v[190:193], v[198:201], v[50:53]
	v_mfma_f32_16x16x32_bf16 v[38:41], v[146:149], v[206:209], v[38:41]
	v_mfma_f32_16x16x32_bf16 v[34:37], v[190:193], v[206:209], v[34:37]
	v_mfma_f32_16x16x32_bf16 v[22:25], v[146:149], v[214:217], v[22:25]
	v_mfma_f32_16x16x32_bf16 v[18:21], v[190:193], v[214:217], v[18:21]
	v_mfma_f32_16x16x32_bf16 v[6:9], v[146:149], v[222:225], v[6:9]
	v_mfma_f32_16x16x32_bf16 v[2:5], v[190:193], v[222:225], v[2:5]
	v_mfma_f32_16x16x32_bf16 v[54:57], v[170:173], v[202:205], v[54:57]
	v_mfma_f32_16x16x32_bf16 v[50:53], v[194:197], v[202:205], v[50:53]
	v_mfma_f32_16x16x32_bf16 v[38:41], v[170:173], v[210:213], v[38:41]
	v_mfma_f32_16x16x32_bf16 v[34:37], v[194:197], v[210:213], v[34:37]
	v_mfma_f32_16x16x32_bf16 v[22:25], v[170:173], v[218:221], v[22:25]
	v_mfma_f32_16x16x32_bf16 v[18:21], v[194:197], v[218:221], v[18:21]
	v_mfma_f32_16x16x32_bf16 v[6:9], v[170:173], v[226:229], v[6:9]
	v_mfma_f32_16x16x32_bf16 v[2:5], v[194:197], v[226:229], v[2:5]
	s_setprio 0
	s_barrier
	s_add_i32 vcc_lo, vcc_lo, 2
	s_add_u32 s10, s10, 0x100
	s_addc_u32 s11, s11, 0
	s_add_u32 s47, s47, 0x100
	s_addc_u32 s63, s63, 0

; #define PG8_STAGE(bufoff, gbase, voff) do { _Pragma("unroll") for (int _i = 0; _i < 2; ++_i) \
;         __builtin_amdgcn_global_load_lds((const unsigned*)((const char*)(gbase) + (voff)[_i]), (PG8_LAS unsigned*)(lds + (bufoff) + ldsw + _i * 8192), 16, 0, 0); } while (0)
; #define PG8_LDA(dst, b, h) do { _Pragma("unroll") for (int m = 0; m < 4; ++m) _Pragma("unroll") for (int k = 0; k < 2; ++k) dst[m][k] = *(const PG8_LAS bf16x8*)(lds + PG8_SA(b, h) + aoff + m * 2048 + k * 1024); } while (0)
; #define PG8_LDB(dst, b, h) do { _Pragma("unroll") for (int n = 0; n < 2; ++n) _Pragma("unroll") for (int k = 0; k < 2; ++k) dst[n][k] = *(const PG8_LAS bf16x8*)(lds + PG8_SB(b, h) + boff + n * 2048 + k * 1024); } while (0)
; #define PG8_SCHED __builtin_amdgcn_sched_barrier(0)
;     __device__ __forceinline__ void operator()(const f32x4 (&acc)[2][2][4][2], const Unit& u, int wr, int wc, int fr, int fq, int) const {
;         const int row0 = u.pm * BM + wr * 64 + fr; const int growt = grow_base + u.pm * BM;
;         const int lane = fq * 16 + fr;
;         if (u.pn < 16) {
;             const int c0 = 64 * u.pn + 16 * wc + 4 * fq;
;             if (growt >= 65536) {
; template <class Epi, class Sched, bool ALIGN_EPI = false, bool SP2 = false>
; __device__ __forceinline__ void gemm_phase(PG8_LAS unsigned char* lds, const Gemm g, const Sched& S, const Epi& E) {
;     ...
;             PG8_LDB(B0, 0, 0); PG8_LDB(B1, 0, 1); PG8_SCHED; PG8_LDA(At, 0, 0); PG8_STAGE(PG8_SA(1, 1), a1 + hstepA, voffA);
.LBB0_249:
	s_add_u32 s100, s28, 0x40080
	s_addc_u32 s101, s21, 0
	v_lshl_add_u64 v[150:151], s[100:101], 0, v[162:163]
	s_add_i32 m0, s17, 0xc000
	s_nop 0
	global_load_lds_dwordx4 v[150:151], off
	v_lshl_add_u64 v[150:151], s[100:101], 0, v[164:165]
	s_add_i32 m0, s17, 0xe000
	s_nop 0
	global_load_lds_dwordx4 v[150:151], off
	s_lshl_b32 s43, s50, 8
	v_add_u32_e32 v134, s43, v178
	s_add_i32 s43, s43, s0
	s_cmp_gt_i32 s20, 15
	s_mov_b64 s[10:11], -1
	s_cbranch_scc0 .LBB0_331
	s_cmp_gt_i32 s43, 0xffff
	s_cselect_b64 s[44:45], -1, 0
	v_ashrrev_i32_e32 v135, 31, v134
	s_mov_b64 s[12:13], -1
	s_and_b64 vcc, exec, s[44:45]
	s_cbranch_vccz .LBB0_252
	v_mad_i64_i32 v[130:131], s[10:11], v134, s34, 0
	s_mov_b64 s[12:13], 0
